# grid barriers after write-through-only phases (G2,G4,G6) skip the L2 writeback
# speedup vs baseline: 1.0031x; 1.0031x over previous
.LBB0_642:
	s_andn2_saveexec_b64 s[16:17], s[16:17]
	s_cbranch_execz .LBB0_662
	s_mov_b64 s[16:17], exec
	s_waitcnt lgkmcnt(0)
	s_waitcnt vmcnt(0)
	v_mbcnt_lo_u32_b32 v0, s16, 0
	v_mbcnt_hi_u32_b32 v0, s17, v0
	v_cmp_eq_u32_e32 vcc, 0, v0
	s_and_saveexec_b64 s[18:19], vcc
	s_cbranch_execz .LBB0_645
	s_bcnt1_i32_b64 s4, s[16:17]
	v_mov_b32_e32 v3, s4
	v_mov_b32_e32 v4, 0xf104000
	global_atomic_add v3, v4, v3, s[12:13] offset:1024 sc0

.LBB0_994:
	s_mov_b64 s[12:13], exec
	s_waitcnt lgkmcnt(0)
	s_waitcnt vmcnt(0)
	v_mbcnt_lo_u32_b32 v0, s12, 0
	v_mbcnt_hi_u32_b32 v0, s13, v0
	v_cmp_eq_u32_e32 vcc, 0, v0
	s_and_saveexec_b64 s[14:15], vcc
	s_cbranch_execz .LBB0_996
	s_bcnt1_i32_b64 s4, s[12:13]
	v_mov_b32_e32 v3, s4
	v_mov_b32_e32 v4, 0xf104000
	global_atomic_add v3, v4, v3, s[8:9] offset:1024 sc0
